# dilated items: touch-prefetch (throw-away dword loads) of the next run's Q rows and first K/V tile rows before the merge/barrier of the current run
# speedup vs baseline: 1.0356x; 1.0005x over previous
.LBB0_279:
	s_add_i32 s82, s75, 1
	s_cmp_gt_u32 s82, 3
	s_cbranch_scc1 .Ltp_skip
	s_min_u32 s83, s82, 2
	s_lshl_b32 s84, s83, 1
	s_lshr_b32 s85, 0x2000, s84
	s_add_i32 s86, s85, -1
	s_lshl_b32 s83, s82, 3
	s_add_i32 s83, s70, s83
	s_cmp_eq_u32 s82, 1
	s_cselect_b32 s83, s71, s83
	s_cselect_b32 s87, s73, s72
	s_cmp_eq_u32 s82, 0
	s_cselect_b32 s88, 0, s83
	s_cselect_b32 s89, s74, s87
	s_cmp_lt_u32 s82, 2
	s_cselect_b64 s[90:91], -1, 0
	v_or_b32_e32 v132, s89, v200
	v_add_u32_e32 v136, s89, v204
	v_lshlrev_b32_e32 v134, s84, v132
	v_cndmask_b32_e64 v132, v132, v136, s[90:91]
	v_add_u32_e32 v134, s88, v134
	v_lshlrev_b32_e32 v132, s84, v132
	v_ashrrev_i32_e32 v135, 31, v134
	v_add_u32_e32 v132, s88, v132
	v_lshlrev_b64 v[134:135], 7, v[134:135]
	v_ashrrev_i32_e32 v133, 31, v132
	v_lshl_add_u64 v[134:135], v[182:183], 0, v[134:135]
	v_lshlrev_b64 v[132:133], 7, v[132:133]
	v_add_u32_e32 v137, s89, v205
	v_lshl_add_u64 v[132:133], v[182:183], 0, v[132:133]
	global_load_dword v238, v[134:135], off
	global_load_dword v238, v[132:133], off
	v_cmp_gt_i32_e32 vcc, 0, v137
	s_nop 0
	v_min_i32_e32 v138, s86, v137
	v_cndmask_b32_e64 v138, v138, 0, vcc
	v_lshlrev_b32_e32 v138, s84, v138
	v_add_u32_e32 v138, s88, v138
	v_ashrrev_i32_e32 v139, 31, v138
	v_lshlrev_b64 v[138:139], 7, v[138:139]
	v_lshl_add_u64 v[140:141], v[128:129], 0, v[138:139]
	v_lshl_add_u64 v[138:139], v[184:185], 0, v[138:139]
	global_load_dword v238, v[140:141], off
	global_load_dword v238, v[138:139], off
	v_or_b32_e32 v138, 8, v137
	v_min_i32_e32 v138, s86, v138
	v_cndmask_b32_e64 v138, v138, 0, vcc
	v_lshlrev_b32_e32 v138, s84, v138
	v_add_u32_e32 v138, s88, v138
	v_ashrrev_i32_e32 v139, 31, v138
	v_lshlrev_b64 v[138:139], 7, v[138:139]
	v_lshl_add_u64 v[140:141], v[128:129], 0, v[138:139]
	v_lshl_add_u64 v[138:139], v[184:185], 0, v[138:139]
	global_load_dword v238, v[140:141], off
	global_load_dword v238, v[138:139], off
	v_or_b32_e32 v138, 16, v137
	v_min_i32_e32 v138, s86, v138
	v_cndmask_b32_e64 v138, v138, 0, vcc
	v_lshlrev_b32_e32 v138, s84, v138
	v_add_u32_e32 v138, s88, v138
	v_ashrrev_i32_e32 v139, 31, v138
	v_lshlrev_b64 v[138:139], 7, v[138:139]
	v_lshl_add_u64 v[140:141], v[128:129], 0, v[138:139]
	v_lshl_add_u64 v[138:139], v[184:185], 0, v[138:139]
	global_load_dword v238, v[140:141], off
	global_load_dword v238, v[138:139], off
	v_or_b32_e32 v138, 24, v137
	v_min_i32_e32 v138, s86, v138
	v_cndmask_b32_e64 v138, v138, 0, vcc
	v_lshlrev_b32_e32 v138, s84, v138
	v_add_u32_e32 v138, s88, v138
	v_ashrrev_i32_e32 v139, 31, v138
	v_lshlrev_b64 v[138:139], 7, v[138:139]
	v_lshl_add_u64 v[140:141], v[128:129], 0, v[138:139]
	v_lshl_add_u64 v[138:139], v[184:185], 0, v[138:139]
	global_load_dword v238, v[140:141], off
	global_load_dword v238, v[138:139], off
